# v2: first map's rows prefetched at the start of the second map's epilogue
# baseline (speedup 1.0000x reference)
.Ldat_fuse:
	v_add3_u32 v18, s25, v194, v195
	s_waitcnt lgkmcnt(0)
	ds_read_b128 v[52:55], v18
	ds_read_b128 v[56:59], v18 offset:1088
	ds_read_b128 v[60:63], v18 offset:2176
	ds_read_b128 v[64:67], v18 offset:3264
	ds_read_b128 v[68:71], v18 offset:4352
	ds_read_b128 v[72:75], v18 offset:5440
	ds_read_b128 v[76:79], v18 offset:6528
	ds_read_b128 v[80:83], v18 offset:7616
	v_mov_b32_e32 v84, 0x358637bd
	s_waitcnt vmcnt(7) lgkmcnt(7)
	v_lshlrev_b32_e32 v10, 16, v116
	v_and_b32_e32 v11, 0xffff0000, v116
	v_lshlrev_b32_e32 v12, 16, v52
	v_and_b32_e32 v13, 0xffff0000, v52
	v_pk_fma_f32 v[2:3], v[236:237], v[12:13], v[10:11] neg_lo:[1,0,0] neg_hi:[1,0,0]
	v_lshlrev_b32_e32 v10, 16, v117
	v_and_b32_e32 v11, 0xffff0000, v117
	v_lshlrev_b32_e32 v12, 16, v53
	v_and_b32_e32 v13, 0xffff0000, v53
	v_pk_fma_f32 v[4:5], v[236:237], v[12:13], v[10:11] neg_lo:[1,0,0] neg_hi:[1,0,0]
	v_lshlrev_b32_e32 v10, 16, v118
	v_and_b32_e32 v11, 0xffff0000, v118
	v_lshlrev_b32_e32 v12, 16, v54
	v_and_b32_e32 v13, 0xffff0000, v54
	v_pk_fma_f32 v[6:7], v[236:237], v[12:13], v[10:11] neg_lo:[1,0,0] neg_hi:[1,0,0]
	v_lshlrev_b32_e32 v10, 16, v119
	v_and_b32_e32 v11, 0xffff0000, v119
	v_lshlrev_b32_e32 v12, 16, v55
	v_and_b32_e32 v13, 0xffff0000, v55
	v_pk_fma_f32 v[8:9], v[236:237], v[12:13], v[10:11] neg_lo:[1,0,0] neg_hi:[1,0,0]
	v_pk_mul_f32 v[14:15], v[2:3], v[2:3]
	v_pk_fma_f32 v[14:15], v[4:5], v[4:5], v[14:15]
	v_pk_fma_f32 v[14:15], v[6:7], v[6:7], v[14:15]
	v_pk_fma_f32 v[14:15], v[8:9], v[8:9], v[14:15]
	s_nop 0
	v_add_f32_e32 v14, v14, v15
	s_nop 1
	v_add_f32_dpp v14, v14, v14 row_ror:8 row_mask:0xf bank_mask:0xf
	s_nop 1
	v_add_f32_dpp v14, v14, v14 row_ror:4 row_mask:0xf bank_mask:0xf
	s_nop 1
	v_add_f32_dpp v14, v14, v14 row_ror:2 row_mask:0xf bank_mask:0xf
	s_nop 1
	v_add_f32_dpp v14, v14, v14 row_ror:1 row_mask:0xf bank_mask:0xf
	v_fmamk_f32 v14, v14, 0x3c000000, v84
	v_rsq_f32_e32 v14, v14
	s_nop 0
	v_pk_mul_f32 v[2:3], v[2:3], v[14:15] op_sel_hi:[1,0]
	v_pk_mul_f32 v[4:5], v[4:5], v[14:15] op_sel_hi:[1,0]
	v_pk_mul_f32 v[6:7], v[6:7], v[14:15] op_sel_hi:[1,0]
	v_pk_mul_f32 v[8:9], v[8:9], v[14:15] op_sel_hi:[1,0]
	v_cvt_pk_bf16_f32 v10, v2, v3
	v_cvt_pk_bf16_f32 v11, v4, v5
	v_cvt_pk_bf16_f32 v12, v6, v7
	v_cvt_pk_bf16_f32 v13, v8, v9
	global_store_dwordx4 v[100:101], v[10:13], off
	s_nop 1
	s_waitcnt vmcnt(7) lgkmcnt(6)
	v_lshlrev_b32_e32 v10, 16, v120
	v_and_b32_e32 v11, 0xffff0000, v120
	v_lshlrev_b32_e32 v12, 16, v56
	v_and_b32_e32 v13, 0xffff0000, v56
	v_pk_fma_f32 v[2:3], v[236:237], v[12:13], v[10:11] neg_lo:[1,0,0] neg_hi:[1,0,0]
	v_lshlrev_b32_e32 v10, 16, v121
	v_and_b32_e32 v11, 0xffff0000, v121
	v_lshlrev_b32_e32 v12, 16, v57
	v_and_b32_e32 v13, 0xffff0000, v57
	v_pk_fma_f32 v[4:5], v[236:237], v[12:13], v[10:11] neg_lo:[1,0,0] neg_hi:[1,0,0]
	v_lshlrev_b32_e32 v10, 16, v122
	v_and_b32_e32 v11, 0xffff0000, v122
	v_lshlrev_b32_e32 v12, 16, v58
	v_and_b32_e32 v13, 0xffff0000, v58
	v_pk_fma_f32 v[6:7], v[236:237], v[12:13], v[10:11] neg_lo:[1,0,0] neg_hi:[1,0,0]
	v_lshlrev_b32_e32 v10, 16, v123
	v_and_b32_e32 v11, 0xffff0000, v123
	v_lshlrev_b32_e32 v12, 16, v59
	v_and_b32_e32 v13, 0xffff0000, v59
	v_pk_fma_f32 v[8:9], v[236:237], v[12:13], v[10:11] neg_lo:[1,0,0] neg_hi:[1,0,0]
	v_pk_mul_f32 v[14:15], v[2:3], v[2:3]
	v_pk_fma_f32 v[14:15], v[4:5], v[4:5], v[14:15]
	v_pk_fma_f32 v[14:15], v[6:7], v[6:7], v[14:15]
	v_pk_fma_f32 v[14:15], v[8:9], v[8:9], v[14:15]
	s_nop 0
	v_add_f32_e32 v14, v14, v15
	s_nop 1
	v_add_f32_dpp v14, v14, v14 row_ror:8 row_mask:0xf bank_mask:0xf
	s_nop 1
	v_add_f32_dpp v14, v14, v14 row_ror:4 row_mask:0xf bank_mask:0xf
	s_nop 1
	v_add_f32_dpp v14, v14, v14 row_ror:2 row_mask:0xf bank_mask:0xf
	s_nop 1
	v_add_f32_dpp v14, v14, v14 row_ror:1 row_mask:0xf bank_mask:0xf
	v_fmamk_f32 v14, v14, 0x3c000000, v84
	v_rsq_f32_e32 v14, v14
	s_nop 0
	v_pk_mul_f32 v[2:3], v[2:3], v[14:15] op_sel_hi:[1,0]
	v_pk_mul_f32 v[4:5], v[4:5], v[14:15] op_sel_hi:[1,0]
	v_pk_mul_f32 v[6:7], v[6:7], v[14:15] op_sel_hi:[1,0]
	v_pk_mul_f32 v[8:9], v[8:9], v[14:15] op_sel_hi:[1,0]
	v_cvt_pk_bf16_f32 v10, v2, v3
	v_cvt_pk_bf16_f32 v11, v4, v5
	v_cvt_pk_bf16_f32 v12, v6, v7
	v_cvt_pk_bf16_f32 v13, v8, v9
	global_store_dwordx4 v[102:103], v[10:13], off
	s_nop 1
	s_waitcnt vmcnt(7) lgkmcnt(5)
	v_lshlrev_b32_e32 v10, 16, v124
	v_and_b32_e32 v11, 0xffff0000, v124
	v_lshlrev_b32_e32 v12, 16, v60
	v_and_b32_e32 v13, 0xffff0000, v60
	v_pk_fma_f32 v[2:3], v[236:237], v[12:13], v[10:11] neg_lo:[1,0,0] neg_hi:[1,0,0]
	v_lshlrev_b32_e32 v10, 16, v125
	v_and_b32_e32 v11, 0xffff0000, v125
	v_lshlrev_b32_e32 v12, 16, v61
	v_and_b32_e32 v13, 0xffff0000, v61
	v_pk_fma_f32 v[4:5], v[236:237], v[12:13], v[10:11] neg_lo:[1,0,0] neg_hi:[1,0,0]
	v_lshlrev_b32_e32 v10, 16, v126
	v_and_b32_e32 v11, 0xffff0000, v126
	v_lshlrev_b32_e32 v12, 16, v62
	v_and_b32_e32 v13, 0xffff0000, v62
	v_pk_fma_f32 v[6:7], v[236:237], v[12:13], v[10:11] neg_lo:[1,0,0] neg_hi:[1,0,0]
	v_lshlrev_b32_e32 v10, 16, v127
	v_and_b32_e32 v11, 0xffff0000, v127
	v_lshlrev_b32_e32 v12, 16, v63
	v_and_b32_e32 v13, 0xffff0000, v63
	v_pk_fma_f32 v[8:9], v[236:237], v[12:13], v[10:11] neg_lo:[1,0,0] neg_hi:[1,0,0]
	v_pk_mul_f32 v[14:15], v[2:3], v[2:3]
	v_pk_fma_f32 v[14:15], v[4:5], v[4:5], v[14:15]
	v_pk_fma_f32 v[14:15], v[6:7], v[6:7], v[14:15]
	v_pk_fma_f32 v[14:15], v[8:9], v[8:9], v[14:15]
	s_nop 0
	v_add_f32_e32 v14, v14, v15
	s_nop 1
	v_add_f32_dpp v14, v14, v14 row_ror:8 row_mask:0xf bank_mask:0xf
	s_nop 1
	v_add_f32_dpp v14, v14, v14 row_ror:4 row_mask:0xf bank_mask:0xf
	s_nop 1
	v_add_f32_dpp v14, v14, v14 row_ror:2 row_mask:0xf bank_mask:0xf
	s_nop 1
	v_add_f32_dpp v14, v14, v14 row_ror:1 row_mask:0xf bank_mask:0xf
	v_fmamk_f32 v14, v14, 0x3c000000, v84
	v_rsq_f32_e32 v14, v14
	s_nop 0
	v_pk_mul_f32 v[2:3], v[2:3], v[14:15] op_sel_hi:[1,0]
	v_pk_mul_f32 v[4:5], v[4:5], v[14:15] op_sel_hi:[1,0]
	v_pk_mul_f32 v[6:7], v[6:7], v[14:15] op_sel_hi:[1,0]
	v_pk_mul_f32 v[8:9], v[8:9], v[14:15] op_sel_hi:[1,0]
	v_cvt_pk_bf16_f32 v10, v2, v3
	v_cvt_pk_bf16_f32 v11, v4, v5
	v_cvt_pk_bf16_f32 v12, v6, v7
	v_cvt_pk_bf16_f32 v13, v8, v9
	global_store_dwordx4 v[104:105], v[10:13], off
	s_nop 1
	s_waitcnt vmcnt(7) lgkmcnt(4)
	v_lshlrev_b32_e32 v10, 16, v128
	v_and_b32_e32 v11, 0xffff0000, v128
	v_lshlrev_b32_e32 v12, 16, v64
	v_and_b32_e32 v13, 0xffff0000, v64
	v_pk_fma_f32 v[2:3], v[236:237], v[12:13], v[10:11] neg_lo:[1,0,0] neg_hi:[1,0,0]
	v_lshlrev_b32_e32 v10, 16, v129
	v_and_b32_e32 v11, 0xffff0000, v129
	v_lshlrev_b32_e32 v12, 16, v65
	v_and_b32_e32 v13, 0xffff0000, v65
	v_pk_fma_f32 v[4:5], v[236:237], v[12:13], v[10:11] neg_lo:[1,0,0] neg_hi:[1,0,0]
	v_lshlrev_b32_e32 v10, 16, v130
	v_and_b32_e32 v11, 0xffff0000, v130
	v_lshlrev_b32_e32 v12, 16, v66
	v_and_b32_e32 v13, 0xffff0000, v66
	v_pk_fma_f32 v[6:7], v[236:237], v[12:13], v[10:11] neg_lo:[1,0,0] neg_hi:[1,0,0]
	v_lshlrev_b32_e32 v10, 16, v131
	v_and_b32_e32 v11, 0xffff0000, v131
	v_lshlrev_b32_e32 v12, 16, v67
	v_and_b32_e32 v13, 0xffff0000, v67
	v_pk_fma_f32 v[8:9], v[236:237], v[12:13], v[10:11] neg_lo:[1,0,0] neg_hi:[1,0,0]
	v_pk_mul_f32 v[14:15], v[2:3], v[2:3]
	v_pk_fma_f32 v[14:15], v[4:5], v[4:5], v[14:15]
	v_pk_fma_f32 v[14:15], v[6:7], v[6:7], v[14:15]
	v_pk_fma_f32 v[14:15], v[8:9], v[8:9], v[14:15]
	s_nop 0
	v_add_f32_e32 v14, v14, v15
	s_nop 1
	v_add_f32_dpp v14, v14, v14 row_ror:8 row_mask:0xf bank_mask:0xf
	s_nop 1
	v_add_f32_dpp v14, v14, v14 row_ror:4 row_mask:0xf bank_mask:0xf
	s_nop 1
	v_add_f32_dpp v14, v14, v14 row_ror:2 row_mask:0xf bank_mask:0xf
	s_nop 1
	v_add_f32_dpp v14, v14, v14 row_ror:1 row_mask:0xf bank_mask:0xf
	v_fmamk_f32 v14, v14, 0x3c000000, v84
	v_rsq_f32_e32 v14, v14
	s_nop 0
	v_pk_mul_f32 v[2:3], v[2:3], v[14:15] op_sel_hi:[1,0]
	v_pk_mul_f32 v[4:5], v[4:5], v[14:15] op_sel_hi:[1,0]
	v_pk_mul_f32 v[6:7], v[6:7], v[14:15] op_sel_hi:[1,0]
	v_pk_mul_f32 v[8:9], v[8:9], v[14:15] op_sel_hi:[1,0]
	v_cvt_pk_bf16_f32 v10, v2, v3
	v_cvt_pk_bf16_f32 v11, v4, v5
	v_cvt_pk_bf16_f32 v12, v6, v7
	v_cvt_pk_bf16_f32 v13, v8, v9
	global_store_dwordx4 v[106:107], v[10:13], off
	s_nop 1
	s_waitcnt vmcnt(7) lgkmcnt(3)
	v_lshlrev_b32_e32 v10, 16, v132
	v_and_b32_e32 v11, 0xffff0000, v132
	v_lshlrev_b32_e32 v12, 16, v68
	v_and_b32_e32 v13, 0xffff0000, v68
	v_pk_fma_f32 v[2:3], v[236:237], v[12:13], v[10:11] neg_lo:[1,0,0] neg_hi:[1,0,0]
	v_lshlrev_b32_e32 v10, 16, v133
	v_and_b32_e32 v11, 0xffff0000, v133
	v_lshlrev_b32_e32 v12, 16, v69
	v_and_b32_e32 v13, 0xffff0000, v69
	v_pk_fma_f32 v[4:5], v[236:237], v[12:13], v[10:11] neg_lo:[1,0,0] neg_hi:[1,0,0]
	v_lshlrev_b32_e32 v10, 16, v134
	v_and_b32_e32 v11, 0xffff0000, v134
	v_lshlrev_b32_e32 v12, 16, v70
	v_and_b32_e32 v13, 0xffff0000, v70
	v_pk_fma_f32 v[6:7], v[236:237], v[12:13], v[10:11] neg_lo:[1,0,0] neg_hi:[1,0,0]
	v_lshlrev_b32_e32 v10, 16, v135
	v_and_b32_e32 v11, 0xffff0000, v135
	v_lshlrev_b32_e32 v12, 16, v71
	v_and_b32_e32 v13, 0xffff0000, v71
	v_pk_fma_f32 v[8:9], v[236:237], v[12:13], v[10:11] neg_lo:[1,0,0] neg_hi:[1,0,0]
	v_pk_mul_f32 v[14:15], v[2:3], v[2:3]
	v_pk_fma_f32 v[14:15], v[4:5], v[4:5], v[14:15]
	v_pk_fma_f32 v[14:15], v[6:7], v[6:7], v[14:15]
	v_pk_fma_f32 v[14:15], v[8:9], v[8:9], v[14:15]
	s_nop 0
	v_add_f32_e32 v14, v14, v15
	s_nop 1
	v_add_f32_dpp v14, v14, v14 row_ror:8 row_mask:0xf bank_mask:0xf
	s_nop 1
	v_add_f32_dpp v14, v14, v14 row_ror:4 row_mask:0xf bank_mask:0xf
	s_nop 1
	v_add_f32_dpp v14, v14, v14 row_ror:2 row_mask:0xf bank_mask:0xf
	s_nop 1
	v_add_f32_dpp v14, v14, v14 row_ror:1 row_mask:0xf bank_mask:0xf
	v_fmamk_f32 v14, v14, 0x3c000000, v84
	v_rsq_f32_e32 v14, v14
	s_nop 0
	v_pk_mul_f32 v[2:3], v[2:3], v[14:15] op_sel_hi:[1,0]
	v_pk_mul_f32 v[4:5], v[4:5], v[14:15] op_sel_hi:[1,0]
	v_pk_mul_f32 v[6:7], v[6:7], v[14:15] op_sel_hi:[1,0]
	v_pk_mul_f32 v[8:9], v[8:9], v[14:15] op_sel_hi:[1,0]
	v_cvt_pk_bf16_f32 v10, v2, v3
	v_cvt_pk_bf16_f32 v11, v4, v5
	v_cvt_pk_bf16_f32 v12, v6, v7
	v_cvt_pk_bf16_f32 v13, v8, v9
	global_store_dwordx4 v[108:109], v[10:13], off
	s_nop 1
	s_waitcnt vmcnt(7) lgkmcnt(2)
	v_lshlrev_b32_e32 v10, 16, v136
	v_and_b32_e32 v11, 0xffff0000, v136
	v_lshlrev_b32_e32 v12, 16, v72
	v_and_b32_e32 v13, 0xffff0000, v72
	v_pk_fma_f32 v[2:3], v[236:237], v[12:13], v[10:11] neg_lo:[1,0,0] neg_hi:[1,0,0]
	v_lshlrev_b32_e32 v10, 16, v137
	v_and_b32_e32 v11, 0xffff0000, v137
	v_lshlrev_b32_e32 v12, 16, v73
	v_and_b32_e32 v13, 0xffff0000, v73
	v_pk_fma_f32 v[4:5], v[236:237], v[12:13], v[10:11] neg_lo:[1,0,0] neg_hi:[1,0,0]
	v_lshlrev_b32_e32 v10, 16, v138
	v_and_b32_e32 v11, 0xffff0000, v138
	v_lshlrev_b32_e32 v12, 16, v74
	v_and_b32_e32 v13, 0xffff0000, v74
	v_pk_fma_f32 v[6:7], v[236:237], v[12:13], v[10:11] neg_lo:[1,0,0] neg_hi:[1,0,0]
	v_lshlrev_b32_e32 v10, 16, v139
	v_and_b32_e32 v11, 0xffff0000, v139
	v_lshlrev_b32_e32 v12, 16, v75
	v_and_b32_e32 v13, 0xffff0000, v75
	v_pk_fma_f32 v[8:9], v[236:237], v[12:13], v[10:11] neg_lo:[1,0,0] neg_hi:[1,0,0]
	v_pk_mul_f32 v[14:15], v[2:3], v[2:3]
	v_pk_fma_f32 v[14:15], v[4:5], v[4:5], v[14:15]
	v_pk_fma_f32 v[14:15], v[6:7], v[6:7], v[14:15]
	v_pk_fma_f32 v[14:15], v[8:9], v[8:9], v[14:15]
	s_nop 0
	v_add_f32_e32 v14, v14, v15
	s_nop 1
	v_add_f32_dpp v14, v14, v14 row_ror:8 row_mask:0xf bank_mask:0xf
	s_nop 1
	v_add_f32_dpp v14, v14, v14 row_ror:4 row_mask:0xf bank_mask:0xf
	s_nop 1
	v_add_f32_dpp v14, v14, v14 row_ror:2 row_mask:0xf bank_mask:0xf
	s_nop 1
	v_add_f32_dpp v14, v14, v14 row_ror:1 row_mask:0xf bank_mask:0xf
	v_fmamk_f32 v14, v14, 0x3c000000, v84
	v_rsq_f32_e32 v14, v14
	s_nop 0
	v_pk_mul_f32 v[2:3], v[2:3], v[14:15] op_sel_hi:[1,0]
	v_pk_mul_f32 v[4:5], v[4:5], v[14:15] op_sel_hi:[1,0]
	v_pk_mul_f32 v[6:7], v[6:7], v[14:15] op_sel_hi:[1,0]
	v_pk_mul_f32 v[8:9], v[8:9], v[14:15] op_sel_hi:[1,0]
	v_cvt_pk_bf16_f32 v10, v2, v3
	v_cvt_pk_bf16_f32 v11, v4, v5
	v_cvt_pk_bf16_f32 v12, v6, v7
	v_cvt_pk_bf16_f32 v13, v8, v9
	global_store_dwordx4 v[110:111], v[10:13], off
	s_nop 1
	s_waitcnt vmcnt(7) lgkmcnt(1)
	v_lshlrev_b32_e32 v10, 16, v140
	v_and_b32_e32 v11, 0xffff0000, v140
	v_lshlrev_b32_e32 v12, 16, v76
	v_and_b32_e32 v13, 0xffff0000, v76
	v_pk_fma_f32 v[2:3], v[236:237], v[12:13], v[10:11] neg_lo:[1,0,0] neg_hi:[1,0,0]
	v_lshlrev_b32_e32 v10, 16, v141
	v_and_b32_e32 v11, 0xffff0000, v141
	v_lshlrev_b32_e32 v12, 16, v77
	v_and_b32_e32 v13, 0xffff0000, v77
	v_pk_fma_f32 v[4:5], v[236:237], v[12:13], v[10:11] neg_lo:[1,0,0] neg_hi:[1,0,0]
	v_lshlrev_b32_e32 v10, 16, v142
	v_and_b32_e32 v11, 0xffff0000, v142
	v_lshlrev_b32_e32 v12, 16, v78
	v_and_b32_e32 v13, 0xffff0000, v78
	v_pk_fma_f32 v[6:7], v[236:237], v[12:13], v[10:11] neg_lo:[1,0,0] neg_hi:[1,0,0]
	v_lshlrev_b32_e32 v10, 16, v143
	v_and_b32_e32 v11, 0xffff0000, v143
	v_lshlrev_b32_e32 v12, 16, v79
	v_and_b32_e32 v13, 0xffff0000, v79
	v_pk_fma_f32 v[8:9], v[236:237], v[12:13], v[10:11] neg_lo:[1,0,0] neg_hi:[1,0,0]
	v_pk_mul_f32 v[14:15], v[2:3], v[2:3]
	v_pk_fma_f32 v[14:15], v[4:5], v[4:5], v[14:15]
	v_pk_fma_f32 v[14:15], v[6:7], v[6:7], v[14:15]
	v_pk_fma_f32 v[14:15], v[8:9], v[8:9], v[14:15]
	s_nop 0
	v_add_f32_e32 v14, v14, v15
	s_nop 1
	v_add_f32_dpp v14, v14, v14 row_ror:8 row_mask:0xf bank_mask:0xf
	s_nop 1
	v_add_f32_dpp v14, v14, v14 row_ror:4 row_mask:0xf bank_mask:0xf
	s_nop 1
	v_add_f32_dpp v14, v14, v14 row_ror:2 row_mask:0xf bank_mask:0xf
	s_nop 1
	v_add_f32_dpp v14, v14, v14 row_ror:1 row_mask:0xf bank_mask:0xf
	v_fmamk_f32 v14, v14, 0x3c000000, v84
	v_rsq_f32_e32 v14, v14
	s_nop 0
	v_pk_mul_f32 v[2:3], v[2:3], v[14:15] op_sel_hi:[1,0]
	v_pk_mul_f32 v[4:5], v[4:5], v[14:15] op_sel_hi:[1,0]
	v_pk_mul_f32 v[6:7], v[6:7], v[14:15] op_sel_hi:[1,0]
	v_pk_mul_f32 v[8:9], v[8:9], v[14:15] op_sel_hi:[1,0]
	v_cvt_pk_bf16_f32 v10, v2, v3
	v_cvt_pk_bf16_f32 v11, v4, v5
	v_cvt_pk_bf16_f32 v12, v6, v7
	v_cvt_pk_bf16_f32 v13, v8, v9
	global_store_dwordx4 v[112:113], v[10:13], off
	s_nop 1
	s_waitcnt vmcnt(7) lgkmcnt(0)
	v_lshlrev_b32_e32 v10, 16, v144
	v_and_b32_e32 v11, 0xffff0000, v144
	v_lshlrev_b32_e32 v12, 16, v80
	v_and_b32_e32 v13, 0xffff0000, v80
	v_pk_fma_f32 v[2:3], v[236:237], v[12:13], v[10:11] neg_lo:[1,0,0] neg_hi:[1,0,0]
	v_lshlrev_b32_e32 v10, 16, v145
	v_and_b32_e32 v11, 0xffff0000, v145
	v_lshlrev_b32_e32 v12, 16, v81
	v_and_b32_e32 v13, 0xffff0000, v81
	v_pk_fma_f32 v[4:5], v[236:237], v[12:13], v[10:11] neg_lo:[1,0,0] neg_hi:[1,0,0]
	v_lshlrev_b32_e32 v10, 16, v146
	v_and_b32_e32 v11, 0xffff0000, v146
	v_lshlrev_b32_e32 v12, 16, v82
	v_and_b32_e32 v13, 0xffff0000, v82
	v_pk_fma_f32 v[6:7], v[236:237], v[12:13], v[10:11] neg_lo:[1,0,0] neg_hi:[1,0,0]
	v_lshlrev_b32_e32 v10, 16, v147
	v_and_b32_e32 v11, 0xffff0000, v147
	v_lshlrev_b32_e32 v12, 16, v83
	v_and_b32_e32 v13, 0xffff0000, v83
	v_pk_fma_f32 v[8:9], v[236:237], v[12:13], v[10:11] neg_lo:[1,0,0] neg_hi:[1,0,0]
	v_pk_mul_f32 v[14:15], v[2:3], v[2:3]
	v_pk_fma_f32 v[14:15], v[4:5], v[4:5], v[14:15]
	v_pk_fma_f32 v[14:15], v[6:7], v[6:7], v[14:15]
	v_pk_fma_f32 v[14:15], v[8:9], v[8:9], v[14:15]
	s_nop 0
	v_add_f32_e32 v14, v14, v15
	s_nop 1
	v_add_f32_dpp v14, v14, v14 row_ror:8 row_mask:0xf bank_mask:0xf
	s_nop 1
	v_add_f32_dpp v14, v14, v14 row_ror:4 row_mask:0xf bank_mask:0xf
	s_nop 1
	v_add_f32_dpp v14, v14, v14 row_ror:2 row_mask:0xf bank_mask:0xf
	s_nop 1
	v_add_f32_dpp v14, v14, v14 row_ror:1 row_mask:0xf bank_mask:0xf
	v_fmamk_f32 v14, v14, 0x3c000000, v84
	v_rsq_f32_e32 v14, v14
	s_nop 0
	v_pk_mul_f32 v[2:3], v[2:3], v[14:15] op_sel_hi:[1,0]
	v_pk_mul_f32 v[4:5], v[4:5], v[14:15] op_sel_hi:[1,0]
	v_pk_mul_f32 v[6:7], v[6:7], v[14:15] op_sel_hi:[1,0]
	v_pk_mul_f32 v[8:9], v[8:9], v[14:15] op_sel_hi:[1,0]
	v_cvt_pk_bf16_f32 v10, v2, v3
	v_cvt_pk_bf16_f32 v11, v4, v5
	v_cvt_pk_bf16_f32 v12, v6, v7
	v_cvt_pk_bf16_f32 v13, v8, v9
	global_store_dwordx4 v[114:115], v[10:13], off
	s_nop 1
	s_add_i32 s40, s40, 1
	s_mov_b64 s[6:7], 0
	s_branch .Ldat_fuse_join
.LBB0_1078:
	s_cmp_lg_u32 s49, 0
	s_cbranch_scc0 .Ldat_nopf
	s_add_u32 s98, s84, s51
	s_addc_u32 s99, s85, 0
	s_lshl_b32 s100, s43, 11
	s_lshr_b32 s101, s43, 21
	s_lshl_b32 s5, s44, 11
	s_or_b32 s101, s101, s5
	s_add_u32 s98, s98, s100
	s_addc_u32 s99, s99, s101
	s_mov_b64 s[100:101], 0x2000
	v_mov_b32_e32 v177, v1
	v_lshl_add_u64 v[100:101], s[98:99], 0, v[176:177]
	v_lshlrev_b32_e32 v102, 11, v190
	v_mov_b32_e32 v103, v1
	v_lshl_add_u64 v[100:101], v[100:101], 0, v[102:103]
	v_lshl_add_u64 v[102:103], v[100:101], 0, s[100:101]
	v_lshl_add_u64 v[104:105], v[102:103], 0, s[100:101]
	v_lshl_add_u64 v[106:107], v[104:105], 0, s[100:101]
	v_lshl_add_u64 v[108:109], v[106:107], 0, s[100:101]
	v_lshl_add_u64 v[110:111], v[108:109], 0, s[100:101]
	v_lshl_add_u64 v[112:113], v[110:111], 0, s[100:101]
	v_lshl_add_u64 v[114:115], v[112:113], 0, s[100:101]
	s_nop 0
	global_load_dwordx4 v[116:119], v[100:101], off
	global_load_dwordx4 v[120:123], v[102:103], off
	global_load_dwordx4 v[124:127], v[104:105], off
	global_load_dwordx4 v[128:131], v[106:107], off
	global_load_dwordx4 v[132:135], v[108:109], off
	global_load_dwordx4 v[136:139], v[110:111], off
	global_load_dwordx4 v[140:143], v[112:113], off
	global_load_dwordx4 v[144:147], v[114:115], off
